# hot loop heads (GEMM K-loops, diff and dilated tile loops) aligned to 64 B, on top of x loads nt
# baseline (speedup 1.0000x reference)
.LBB0_132:
	s_ashr_i32 s59, s58, 31
	s_lshl_b64 s[28:29], s[58:59], 19
	s_add_u32 s60, s18, s28
	s_addc_u32 s61, s19, s29
	s_and_b64 s[28:29], s[0:1], exec
	s_cselect_b32 s5, s61, s67
	s_cselect_b32 s59, s60, s66
	s_ashr_i32 s57, s56, 31
	s_lshl_b64 s[28:29], s[56:57], 19
	s_add_u32 s62, s6, s28
	s_addc_u32 s63, s7, s29
	s_and_b64 s[28:29], s[0:1], exec
	s_cselect_b32 s57, s63, s69
	s_cselect_b32 s65, s62, s68
	s_add_u32 s66, s66, 0x40080
	s_addc_u32 s67, s67, 0
	s_add_u32 s88, s68, 0x100
	v_mov_b32_e32 v0, 0
	s_addc_u32 s89, s69, 0
	s_mov_b32 s90, -2
	v_mov_b32_e32 v1, v0
	v_mov_b32_e32 v2, v0
	v_mov_b32_e32 v3, v0
	v_mov_b32_e32 v4, v0
	v_mov_b32_e32 v5, v0
	v_mov_b32_e32 v6, v0
	v_mov_b32_e32 v7, v0
	v_mov_b32_e32 v12, v0
	v_mov_b32_e32 v13, v0
	v_mov_b32_e32 v14, v0
	v_mov_b32_e32 v15, v0
	v_mov_b32_e32 v20, v0
	v_mov_b32_e32 v21, v0
	v_mov_b32_e32 v22, v0
	v_mov_b32_e32 v23, v0
	v_mov_b32_e32 v28, v0
	v_mov_b32_e32 v29, v0
	v_mov_b32_e32 v30, v0
	v_mov_b32_e32 v31, v0
	v_mov_b32_e32 v36, v0
	v_mov_b32_e32 v37, v0
	v_mov_b32_e32 v38, v0
	v_mov_b32_e32 v39, v0
	v_mov_b32_e32 v44, v0
	v_mov_b32_e32 v45, v0
	v_mov_b32_e32 v46, v0
	v_mov_b32_e32 v47, v0
	v_mov_b32_e32 v52, v0
	v_mov_b32_e32 v53, v0
	v_mov_b32_e32 v54, v0
	v_mov_b32_e32 v55, v0
	v_mov_b32_e32 v8, v0
	v_mov_b32_e32 v9, v0
	v_mov_b32_e32 v10, v0
	v_mov_b32_e32 v11, v0
	v_mov_b32_e32 v16, v0
	v_mov_b32_e32 v17, v0
	v_mov_b32_e32 v18, v0
	v_mov_b32_e32 v19, v0
	v_mov_b32_e32 v24, v0
	v_mov_b32_e32 v25, v0
	v_mov_b32_e32 v26, v0
	v_mov_b32_e32 v27, v0
	v_mov_b32_e32 v32, v0
	v_mov_b32_e32 v33, v0
	v_mov_b32_e32 v34, v0
	v_mov_b32_e32 v35, v0
	v_mov_b32_e32 v40, v0
	v_mov_b32_e32 v41, v0
	v_mov_b32_e32 v42, v0
	v_mov_b32_e32 v43, v0
	v_mov_b32_e32 v48, v0
	v_mov_b32_e32 v49, v0
	v_mov_b32_e32 v50, v0
	v_mov_b32_e32 v51, v0
	v_mov_b32_e32 v56, v0
	v_mov_b32_e32 v57, v0
	v_mov_b32_e32 v58, v0
	v_mov_b32_e32 v59, v0
	v_mov_b32_e32 v60, v0
	v_mov_b32_e32 v61, v0
	v_mov_b32_e32 v62, v0
	v_mov_b32_e32 v63, v0
	v_mov_b32_e32 v64, v0
	v_mov_b32_e32 v65, v0
	v_mov_b32_e32 v66, v0
	v_mov_b32_e32 v67, v0
	v_mov_b32_e32 v68, v0
	v_mov_b32_e32 v69, v0
	v_mov_b32_e32 v70, v0
	v_mov_b32_e32 v71, v0
	v_mov_b32_e32 v76, v0
	v_mov_b32_e32 v77, v0
	v_mov_b32_e32 v78, v0
	v_mov_b32_e32 v79, v0
	v_mov_b32_e32 v84, v0
	v_mov_b32_e32 v85, v0
	v_mov_b32_e32 v86, v0
	v_mov_b32_e32 v87, v0
	v_mov_b32_e32 v92, v0
	v_mov_b32_e32 v93, v0
	v_mov_b32_e32 v94, v0
	v_mov_b32_e32 v95, v0
	v_mov_b32_e32 v100, v0
	v_mov_b32_e32 v101, v0
	v_mov_b32_e32 v102, v0
	v_mov_b32_e32 v103, v0
	v_mov_b32_e32 v108, v0
	v_mov_b32_e32 v109, v0
	v_mov_b32_e32 v110, v0
	v_mov_b32_e32 v111, v0
	v_mov_b32_e32 v116, v0
	v_mov_b32_e32 v117, v0
	v_mov_b32_e32 v118, v0
	v_mov_b32_e32 v119, v0
	v_mov_b32_e32 v72, v0
	v_mov_b32_e32 v73, v0
	v_mov_b32_e32 v74, v0
	v_mov_b32_e32 v75, v0
	v_mov_b32_e32 v80, v0
	v_mov_b32_e32 v81, v0
	v_mov_b32_e32 v82, v0
	v_mov_b32_e32 v83, v0
	v_mov_b32_e32 v88, v0
	v_mov_b32_e32 v89, v0
	v_mov_b32_e32 v90, v0
	v_mov_b32_e32 v91, v0
	v_mov_b32_e32 v96, v0
	v_mov_b32_e32 v97, v0
	v_mov_b32_e32 v98, v0
	v_mov_b32_e32 v99, v0
	v_mov_b32_e32 v104, v0
	v_mov_b32_e32 v105, v0
	v_mov_b32_e32 v106, v0
	v_mov_b32_e32 v107, v0
	v_mov_b32_e32 v112, v0
	v_mov_b32_e32 v113, v0
	v_mov_b32_e32 v114, v0
	v_mov_b32_e32 v115, v0
	v_mov_b32_e32 v120, v0
	v_mov_b32_e32 v121, v0
	v_mov_b32_e32 v122, v0
	v_mov_b32_e32 v123, v0
	v_mov_b32_e32 v124, v0
	v_mov_b32_e32 v125, v0
	v_mov_b32_e32 v126, v0
	v_mov_b32_e32 v127, v0
	.p2align	6

.LBB0_255:
	s_sub_i32 s8, 4, s76
	v_lshlrev_b32_e32 v34, 1, v34
	v_cvt_f32_ubyte0_e32 v38, s8
	v_lshlrev_b32_e32 v158, 3, v33
	v_and_b32_e32 v34, 2, v34
	v_and_b32_e32 v37, 1, v37
	v_lshlrev_b32_e32 v33, 1, v33
	v_mul_f32_e32 v38, -2.0, v38
	v_bitop3_b32 v40, v34, v33, v37 bitop3:0x36
	v_or_b32_e32 v33, 1, v33
	v_exp_f32_e32 v38, v38
	v_and_b32_e32 v157, 63, v32
	v_bitop3_b32 v33, v34, v33, v37 bitop3:0x36
	v_cvt_f32_ubyte0_e32 v34, v35
	v_cvt_pk_bf16_f32 v34, v34, v34
	v_cmp_gt_u32_e32 vcc, 32, v157
	v_mul_f32_e32 v160, 0x3fb8aa3b, v38
	s_add_i32 s80, s75, 0xc000
	v_cndmask_b32_e32 v152, 0, v34, vcc
	v_or_b32_e32 v34, 32, v35
	v_cvt_f32_ubyte0_e32 v34, v34
	v_cvt_pk_bf16_f32 v34, v34, v34
	v_cndmask_b32_e32 v148, 0, v34, vcc
	v_cvt_pk_bf16_f32 v34, v160, 0
	v_lshlrev_b32_e32 v34, 16, v34
	v_fma_f32 v35, v38, s39, -v34
	v_cvt_pk_bf16_f32 v35, v35, 0
	v_lshlrev_b32_e32 v35, 16, v35
	v_cvt_pk_bf16_f32 v186, v34, v35
	v_xor_b32_e32 v34, 0x80000000, v34
	v_xor_b32_e32 v35, 0x80000000, v35
	v_cvt_pk_bf16_f32 v187, v34, v35
	v_or_b32_e32 v34, s5, v158
	v_sub_u32_e32 v35, v159, v34
	v_xad_u32 v34, v34, -1, v159
	v_cvt_f32_i32_e32 v34, v34
	v_add_u32_e32 v38, -2, v35
	v_add_u32_e32 v44, -3, v35
	v_cvt_f32_i32_e32 v37, v35
	v_cvt_f32_i32_e32 v38, v38
	v_cvt_f32_i32_e32 v44, v44
	v_fma_f32 v17, -v160, |v34|, v17
	v_add_u32_e32 v34, -4, v35
	v_cvt_f32_i32_e32 v34, v34
	v_fma_f32 v16, -v160, |v37|, v16
	v_fma_f32 v18, -v160, |v38|, v18
	v_fma_f32 v19, -v160, |v44|, v19
	v_add_u32_e32 v37, -5, v35
	v_add_u32_e32 v38, -6, v35
	v_add_u32_e32 v44, -7, v35
	v_cvt_f32_i32_e32 v37, v37
	v_cvt_f32_i32_e32 v38, v38
	v_cvt_f32_i32_e32 v44, v44
	v_fma_f32 v34, -v160, |v34|, v20
	v_add_u32_e32 v20, -16, v35
	v_cvt_f32_i32_e32 v20, v20
	v_fma_f32 v37, -v160, |v37|, v21
	v_fma_f32 v38, -v160, |v38|, v22
	v_fma_f32 v44, -v160, |v44|, v23
	v_subrev_u32_e32 v21, 17, v35
	v_subrev_u32_e32 v22, 18, v35
	v_subrev_u32_e32 v23, 19, v35
	v_cvt_f32_i32_e32 v21, v21
	v_cvt_f32_i32_e32 v22, v22
	v_cvt_f32_i32_e32 v23, v23
	v_fma_f32 v45, -v160, |v20|, v24
	v_subrev_u32_e32 v20, 20, v35
	v_cvt_f32_i32_e32 v20, v20
	v_fma_f32 v46, -v160, |v21|, v25
	v_fma_f32 v47, -v160, |v22|, v26
	v_fma_f32 v48, -v160, |v23|, v27
	v_subrev_u32_e32 v21, 21, v35
	v_subrev_u32_e32 v22, 22, v35
	v_subrev_u32_e32 v23, 23, v35
	v_cvt_f32_i32_e32 v21, v21
	v_cvt_f32_i32_e32 v22, v22
	v_cvt_f32_i32_e32 v23, v23
	v_fma_f32 v49, -v160, |v20|, v28
	v_subrev_u32_e32 v20, 32, v35
	v_cvt_f32_i32_e32 v20, v20
	v_fma_f32 v50, -v160, |v21|, v29
	v_fma_f32 v51, -v160, |v22|, v30
	v_fma_f32 v52, -v160, |v23|, v31
	v_subrev_u32_e32 v21, 33, v35
	v_subrev_u32_e32 v22, 34, v35
	v_subrev_u32_e32 v23, 35, v35
	v_cvt_f32_i32_e32 v21, v21
	v_cvt_f32_i32_e32 v22, v22
	v_cvt_f32_i32_e32 v23, v23
	v_fma_f32 v53, -v160, |v20|, v0
	v_subrev_u32_e32 v0, 36, v35
	v_cvt_f32_i32_e32 v0, v0
	v_fma_f32 v54, -v160, |v21|, v1
	v_fma_f32 v120, -v160, |v22|, v2
	v_fma_f32 v121, -v160, |v23|, v3
	v_subrev_u32_e32 v1, 37, v35
	v_subrev_u32_e32 v2, 38, v35
	v_subrev_u32_e32 v3, 39, v35
	v_cvt_f32_i32_e32 v1, v1
	v_cvt_f32_i32_e32 v2, v2
	v_cvt_f32_i32_e32 v3, v3
	v_fma_f32 v122, -v160, |v0|, v4
	v_subrev_u32_e32 v0, 48, v35
	v_cvt_f32_i32_e32 v0, v0
	v_fma_f32 v123, -v160, |v1|, v5
	v_fma_f32 v124, -v160, |v2|, v6
	v_fma_f32 v125, -v160, |v3|, v7
	v_subrev_u32_e32 v1, 49, v35
	v_subrev_u32_e32 v2, 50, v35
	v_subrev_u32_e32 v3, 51, v35
	v_cvt_f32_i32_e32 v1, v1
	v_cvt_f32_i32_e32 v2, v2
	v_cvt_f32_i32_e32 v3, v3
	v_fma_f32 v128, -v160, |v0|, v8
	v_subrev_u32_e32 v0, 52, v35
	v_cvt_f32_i32_e32 v0, v0
	v_fma_f32 v129, -v160, |v1|, v9
	v_fma_f32 v130, -v160, |v2|, v10
	v_fma_f32 v192, -v160, |v3|, v11
	v_subrev_u32_e32 v1, 53, v35
	v_subrev_u32_e32 v2, 54, v35
	v_subrev_u32_e32 v3, 55, v35
	v_cvt_f32_i32_e32 v1, v1
	v_cvt_f32_i32_e32 v2, v2
	v_cvt_f32_i32_e32 v3, v3
	s_lshl_b32 s5, s4, 14
	v_fma_f32 v204, -v160, |v0|, v12
	v_add_u32_e32 v0, s5, v170
	s_mov_b32 s8, m0
	s_mov_b32 m0, s80
	s_nop 0
	global_load_lds_dwordx4 v0, s[6:7]
	s_mov_b32 m0, s8
	v_add_u32_e32 v0, s5, v169
	s_add_i32 s81, s75, 0xe000
	s_mov_b32 s5, m0
	s_mov_b32 m0, s81
	s_nop 0
	global_load_lds_dwordx4 v0, s[6:7]
	s_mov_b32 m0, s5
	v_exp_f32_e32 v35, v16
	v_fma_f32 v205, -v160, |v1|, v13
	v_fma_f32 v206, -v160, |v2|, v14
	v_fma_f32 v207, -v160, |v3|, v15
	ds_read_b128 v[0:3], v171 offset:32768
	ds_read_b128 v[4:7], v171 offset:36864
	ds_read_b128 v[8:11], v174 offset:32768
	ds_read_b128 v[12:15], v174 offset:36864
	v_exp_f32_e32 v55, v17
	v_exp_f32_e32 v56, v18
	v_exp_f32_e32 v57, v19
	v_add_f32_e32 v16, 0, v35
	v_lshrrev_b32_e32 v36, 2, v36
	v_add_f32_e32 v16, v55, v16
	v_or_b32_e32 v39, v158, v36
	v_lshlrev_b32_e32 v32, 3, v32
	v_lshlrev_b32_e32 v36, 6, v36
	v_cndmask_b32_e32 v154, 0, v196, vcc
	v_cndmask_b32_e32 v153, 0, v197, vcc
	v_add_f32_e32 v16, v56, v16
	s_mov_b32 s76, 2
	v_and_b32_e32 v32, 8, v32
	v_xor_b32_e32 v41, 64, v36
	v_xor_b32_e32 v42, 0x80, v36
	v_xor_b32_e32 v43, 0xc0, v36
	v_lshlrev_b32_e32 v33, 4, v33
	v_mov_b32_e32 v155, v131
	v_mov_b32_e32 v149, v153
	v_mov_b32_e32 v150, v154
	v_mov_b32_e32 v151, v131
	v_add_f32_e32 v58, v57, v16
	s_waitcnt lgkmcnt(3)
	v_mfma_f32_32x32x16_bf16 v[80:95], v[0:3], v[144:147], 0
	ds_read_b128 v[16:19], v172 offset:32768
	ds_read_b128 v[20:23], v172 offset:36864
	ds_read_b128 v[24:27], v173 offset:32768
	ds_read_b128 v[28:31], v173 offset:36864
	v_exp_f32_e32 v34, v34
	v_exp_f32_e32 v37, v37
	v_add_f32_e32 v0, v34, v58
	v_add_f32_e32 v2, v37, v0
	s_waitcnt lgkmcnt(6)
	v_mfma_f32_32x32x16_bf16 v[64:79], v[4:7], v[144:147], 0
	v_exp_f32_e32 v3, v38
	v_exp_f32_e32 v38, v44
	v_cvt_pk_bf16_f32 v0, v35, v55
	v_cvt_pk_bf16_f32 v1, v56, v57
	v_add_f32_e32 v2, v3, v2
	v_add_f32_e32 v35, v38, v2
	v_cvt_pk_bf16_f32 v2, v34, v37
	v_cvt_pk_bf16_f32 v3, v3, v38
	s_waitcnt lgkmcnt(5)
	v_mfma_f32_32x32x16_bf16 v[80:95], v[8:11], v[140:143], v[80:95]
	v_exp_f32_e32 v34, v45
	v_exp_f32_e32 v37, v46
	v_add_f32_e32 v4, v34, v35
	v_add_f32_e32 v4, v37, v4
	s_waitcnt lgkmcnt(4)
	v_mfma_f32_32x32x16_bf16 v[64:79], v[12:15], v[140:143], v[64:79]
	v_exp_f32_e32 v35, v47
	v_exp_f32_e32 v38, v48
	v_add_f32_e32 v4, v35, v4
	v_add_f32_e32 v44, v38, v4
	v_lshl_or_b32 v4, v39, 8, v32
	v_lshl_or_b32 v12, v40, 4, v4
	v_or_b32_e32 v165, v12, v36
	v_add_u32_e32 v13, 0x400, v4
	v_or_b32_e32 v161, v12, v42
	v_add_u32_e32 v175, 0, v165
	v_or3_b32 v166, v33, v36, v13
	v_or_b32_e32 v167, v12, v41
	v_or3_b32 v168, v33, v41, v13
	v_add_u32_e32 v179, 0, v161
	v_or3_b32 v162, v33, v42, v13
	v_or_b32_e32 v163, v12, v43
	v_or3_b32 v164, v33, v43, v13
	s_waitcnt lgkmcnt(3)
	v_mfma_f32_32x32x16_bf16 v[80:95], v[16:19], v[136:139], v[80:95]
	v_add_u32_e32 v176, 0, v166
	v_add_u32_e32 v177, 0, v167
	v_add_u32_e32 v178, 0, v168
	ds_read_b64_tr_b16 v[4:5], v175 offset:16384
	ds_read_b64_tr_b16 v[6:7], v176 offset:16384
	ds_read_b64_tr_b16 v[8:9], v177 offset:16384
	ds_read_b64_tr_b16 v[10:11], v178 offset:16384
	v_add_u32_e32 v182, 0, v162
	v_add_u32_e32 v183, 0, v163
	v_add_u32_e32 v184, 0, v164
	ds_read_b64_tr_b16 v[12:13], v179 offset:16384
	ds_read_b64_tr_b16 v[14:15], v182 offset:16384
	ds_read_b64_tr_b16 v[96:97], v183 offset:16384
	ds_read_b64_tr_b16 v[98:99], v184 offset:16384
	v_exp_f32_e32 v32, v49
	v_exp_f32_e32 v33, v50
	v_add_f32_e32 v16, v32, v44
	v_add_f32_e32 v16, v33, v16
	s_waitcnt lgkmcnt(10)
	v_mfma_f32_32x32x16_bf16 v[64:79], v[20:23], v[136:139], v[64:79]
	v_exp_f32_e32 v17, v51
	v_exp_f32_e32 v18, v52
	v_cvt_pk_bf16_f32 v100, v34, v37
	v_cvt_pk_bf16_f32 v101, v35, v38
	v_add_f32_e32 v16, v17, v16
	v_add_f32_e32 v16, v18, v16
	v_cvt_pk_bf16_f32 v102, v32, v33
	v_cvt_pk_bf16_f32 v103, v17, v18
	s_waitcnt lgkmcnt(9)
	v_mfma_f32_32x32x16_bf16 v[80:95], v[24:27], v[132:135], v[80:95]
	s_waitcnt lgkmcnt(8)
	v_mfma_f32_32x32x16_bf16 v[64:79], v[28:31], v[132:135], v[64:79]
	ds_read_b64_tr_b16 v[104:105], v175 offset:20480
	ds_read_b64_tr_b16 v[106:107], v176 offset:20480
	ds_read_b64_tr_b16 v[108:109], v177 offset:20480
	ds_read_b64_tr_b16 v[110:111], v178 offset:20480
	ds_read_b64_tr_b16 v[112:113], v179 offset:20480
	ds_read_b64_tr_b16 v[114:115], v182 offset:20480
	ds_read_b64_tr_b16 v[116:117], v183 offset:20480
	ds_read_b64_tr_b16 v[118:119], v184 offset:20480
	v_exp_f32_e32 v126, v53
	v_exp_f32_e32 v127, v54
	s_waitcnt lgkmcnt(14)
	v_mfma_f32_32x32x16_bf16 v[48:63], v[4:7], v[0:3], 0
	v_lshl_or_b32 v17, s4, 6, v158
	v_add_f32_e32 v4, v126, v16
	v_add_f32_e32 v4, v127, v4
	v_sub_u32_e32 v208, v159, v17
	v_add_u32_e32 v209, -1, v208
	s_waitcnt lgkmcnt(12)
	v_mfma_f32_32x32x16_bf16 v[32:47], v[8:11], v[0:3], 0
	v_exp_f32_e32 v5, v120
	v_exp_f32_e32 v6, v121
	v_add_u32_e32 v210, -3, v208
	v_add_u32_e32 v211, -2, v208
	v_add_f32_e32 v4, v5, v4
	v_add_f32_e32 v4, v6, v4
	s_waitcnt lgkmcnt(10)
	v_mfma_f32_32x32x16_bf16 v[16:31], v[12:15], v[0:3], 0
	v_exp_f32_e32 v122, v122
	v_exp_f32_e32 v123, v123
	v_add_u32_e32 v212, -5, v208
	v_add_u32_e32 v213, -4, v208
	v_add_f32_e32 v4, v122, v4
	v_add_f32_e32 v4, v123, v4
	v_exp_f32_e32 v124, v124
	v_exp_f32_e32 v125, v125
	v_cvt_pk_bf16_f32 v121, v5, v6
	v_cvt_pk_bf16_f32 v120, v126, v127
	v_add_f32_e32 v4, v124, v4
	v_add_f32_e32 v214, v125, v4
	s_waitcnt lgkmcnt(8)
	v_mfma_f32_32x32x16_bf16 v[0:15], v[96:99], v[0:3], 0
	v_cvt_pk_bf16_f32 v122, v122, v123
	v_cvt_pk_bf16_f32 v123, v124, v125
	v_add_u32_e32 v215, -7, v208
	v_add_u32_e32 v216, -6, v208
	ds_read_b64_tr_b16 v[96:97], v175 offset:24576
	ds_read_b64_tr_b16 v[98:99], v176 offset:24576
	ds_read_b64_tr_b16 v[124:125], v177 offset:24576
	ds_read_b64_tr_b16 v[126:127], v178 offset:24576
	ds_read_b64_tr_b16 v[188:189], v179 offset:24576
	ds_read_b64_tr_b16 v[190:191], v182 offset:24576
	ds_read_b64_tr_b16 v[200:201], v183 offset:24576
	ds_read_b64_tr_b16 v[202:203], v184 offset:24576
	s_waitcnt lgkmcnt(14)
	v_mfma_f32_32x32x16_bf16 v[48:63], v[104:107], v[100:103], v[48:63]
	v_exp_f32_e32 v128, v128
	v_subrev_u32_e32 v105, 17, v208
	v_add_u32_e32 v106, -16, v208
	v_add_f32_e32 v104, v128, v214
	s_waitcnt lgkmcnt(12)
	v_mfma_f32_32x32x16_bf16 v[32:47], v[108:111], v[100:103], v[32:47]
	v_exp_f32_e32 v129, v129
	v_subrev_u32_e32 v107, 19, v208
	v_subrev_u32_e32 v214, 18, v208
	v_add_f32_e32 v104, v129, v104
	s_waitcnt lgkmcnt(10)
	v_mfma_f32_32x32x16_bf16 v[16:31], v[112:115], v[100:103], v[16:31]
	v_exp_f32_e32 v130, v130
	v_subrev_u32_e32 v108, 21, v208
	v_subrev_u32_e32 v109, 20, v208
	v_add_f32_e32 v104, v130, v104
	v_exp_f32_e32 v192, v192
	s_waitcnt lgkmcnt(8)
	v_mfma_f32_32x32x16_bf16 v[0:15], v[116:119], v[100:103], v[0:15]
	v_subrev_u32_e32 v110, 23, v208
	v_subrev_u32_e32 v111, 22, v208
	v_cvt_f32_i32_e32 v114, v111
	v_add_f32_e32 v217, v192, v104
	v_cvt_f32_i32_e32 v115, v110
	v_cvt_f32_i32_e32 v112, v109
	v_cvt_f32_i32_e32 v113, v108
	v_cvt_f32_i32_e32 v110, v214
	v_cvt_f32_i32_e32 v111, v107
	v_cvt_f32_i32_e32 v108, v106
	v_cvt_f32_i32_e32 v109, v105
	v_cvt_f32_i32_e32 v106, v216
	v_cvt_f32_i32_e32 v107, v215
	v_cvt_f32_i32_e32 v104, v213
	v_cvt_f32_i32_e32 v105, v212
	v_cvt_f32_i32_e32 v100, v208
	v_cvt_f32_i32_e32 v101, v209
	v_cvt_f32_i32_e32 v102, v210
	v_cvt_f32_i32_e32 v116, v211
	v_and_b32_e32 v100, 0x7fffffff, v100
	v_and_b32_e32 v101, 0x7fffffff, v101
	v_and_b32_e32 v103, 0x7fffffff, v102
	v_and_b32_e32 v102, 0x7fffffff, v116
	v_and_b32_e32 v105, 0x7fffffff, v105
	v_and_b32_e32 v104, 0x7fffffff, v104
	v_and_b32_e32 v107, 0x7fffffff, v107
	v_and_b32_e32 v106, 0x7fffffff, v106
	v_and_b32_e32 v109, 0x7fffffff, v109
	v_and_b32_e32 v108, 0x7fffffff, v108
	v_and_b32_e32 v111, 0x7fffffff, v111
	v_and_b32_e32 v110, 0x7fffffff, v110
	v_and_b32_e32 v113, 0x7fffffff, v113
	v_and_b32_e32 v112, 0x7fffffff, v112
	v_and_b32_e32 v115, 0x7fffffff, v115
	v_and_b32_e32 v114, 0x7fffffff, v114
	v_pk_fma_f32 v[94:95], v[160:161], v[114:115], v[94:95] op_sel_hi:[0,1,1] neg_lo:[1,0,0] neg_hi:[1,0,0]
	v_pk_fma_f32 v[92:93], v[160:161], v[112:113], v[92:93] op_sel_hi:[0,1,1] neg_lo:[1,0,0] neg_hi:[1,0,0]
	v_pk_fma_f32 v[90:91], v[160:161], v[110:111], v[90:91] op_sel_hi:[0,1,1] neg_lo:[1,0,0] neg_hi:[1,0,0]
	v_pk_fma_f32 v[88:89], v[160:161], v[108:109], v[88:89] op_sel_hi:[0,1,1] neg_lo:[1,0,0] neg_hi:[1,0,0]
	v_pk_fma_f32 v[86:87], v[160:161], v[106:107], v[86:87] op_sel_hi:[0,1,1] neg_lo:[1,0,0] neg_hi:[1,0,0]
	v_pk_fma_f32 v[84:85], v[160:161], v[104:105], v[84:85] op_sel_hi:[0,1,1] neg_lo:[1,0,0] neg_hi:[1,0,0]
	v_pk_fma_f32 v[82:83], v[160:161], v[102:103], v[82:83] op_sel_hi:[0,1,1] neg_lo:[1,0,0] neg_hi:[1,0,0]
	v_pk_fma_f32 v[80:81], v[160:161], v[100:101], v[80:81] op_sel_hi:[0,1,1] neg_lo:[1,0,0] neg_hi:[1,0,0]
	ds_read_b64_tr_b16 v[100:101], v175 offset:28672
	ds_read_b64_tr_b16 v[102:103], v176 offset:28672
	ds_read_b64_tr_b16 v[104:105], v177 offset:28672
	ds_read_b64_tr_b16 v[106:107], v178 offset:28672
	ds_read_b64_tr_b16 v[108:109], v179 offset:28672
	ds_read_b64_tr_b16 v[110:111], v182 offset:28672
	ds_read_b64_tr_b16 v[112:113], v183 offset:28672
	ds_read_b64_tr_b16 v[114:115], v184 offset:28672
	s_waitcnt lgkmcnt(14)
	v_mfma_f32_32x32x16_bf16 v[48:63], v[96:99], v[120:123], v[48:63]
	v_exp_f32_e32 v116, v204
	s_nop 0
	v_add_f32_e32 v96, v116, v217
	s_waitcnt lgkmcnt(12)
	v_mfma_f32_32x32x16_bf16 v[32:47], v[124:127], v[120:123], v[32:47]
	v_exp_f32_e32 v98, v205
	s_nop 0
	v_add_f32_e32 v96, v98, v96
	s_waitcnt lgkmcnt(10)
	v_mfma_f32_32x32x16_bf16 v[16:31], v[188:191], v[120:123], v[16:31]
	v_exp_f32_e32 v99, v206
	s_nop 0
	v_add_f32_e32 v117, v99, v96
	s_waitcnt lgkmcnt(8)
	v_mfma_f32_32x32x16_bf16 v[0:15], v[200:203], v[120:123], v[0:15]
	v_exp_f32_e32 v118, v207
	v_cvt_pk_bf16_f32 v96, v128, v129
	v_cvt_pk_bf16_f32 v97, v130, v192
	v_cvt_pk_bf16_f32 v98, v116, v98
	v_add_f32_e32 v116, v118, v117
	v_cvt_pk_bf16_f32 v99, v99, v118
	s_waitcnt lgkmcnt(6)
	s_nop 0
	v_mfma_f32_32x32x16_bf16 v[48:63], v[100:103], v[96:99], v[48:63]
	s_waitcnt lgkmcnt(4)
	v_mfma_f32_32x32x16_bf16 v[32:47], v[104:107], v[96:99], v[32:47]
	s_waitcnt lgkmcnt(2)
	v_mfma_f32_32x32x16_bf16 v[16:31], v[108:111], v[96:99], v[16:31]
	s_waitcnt lgkmcnt(0)
	v_mfma_f32_32x32x16_bf16 v[0:15], v[112:115], v[96:99], v[0:15]
	v_subrev_u32_e32 v100, 33, v208
	v_subrev_u32_e32 v101, 32, v208
	v_subrev_u32_e32 v102, 35, v208
	v_subrev_u32_e32 v103, 34, v208
	v_subrev_u32_e32 v104, 37, v208
	v_subrev_u32_e32 v105, 36, v208
	v_subrev_u32_e32 v96, 39, v208
	v_subrev_u32_e32 v97, 38, v208
	v_subrev_u32_e32 v98, 49, v208
	v_subrev_u32_e32 v99, 48, v208
	v_subrev_u32_e32 v106, 51, v208
	v_subrev_u32_e32 v107, 50, v208
	v_subrev_u32_e32 v108, 53, v208
	v_subrev_u32_e32 v109, 52, v208
	v_subrev_u32_e32 v110, 55, v208
	v_subrev_u32_e32 v111, 54, v208
	v_cvt_f32_i32_e32 v112, v111
	v_cvt_f32_i32_e32 v110, v110
	v_cvt_f32_i32_e32 v111, v109
	v_cvt_f32_i32_e32 v108, v108
	v_cvt_f32_i32_e32 v109, v107
	v_cvt_f32_i32_e32 v106, v106
	v_cvt_f32_i32_e32 v107, v99
	v_cvt_f32_i32_e32 v113, v98
	v_cvt_f32_i32_e32 v114, v97
	v_cvt_f32_i32_e32 v115, v96
	v_cvt_f32_i32_e32 v105, v105
	v_cvt_f32_i32_e32 v104, v104
	v_cvt_f32_i32_e32 v96, v100
	v_cvt_f32_i32_e32 v98, v101
	v_cvt_f32_i32_e32 v99, v102
	v_cvt_f32_i32_e32 v100, v103
	v_and_b32_e32 v97, 0x7fffffff, v96
	v_and_b32_e32 v96, 0x7fffffff, v98
	v_and_b32_e32 v99, 0x7fffffff, v99
	v_and_b32_e32 v98, 0x7fffffff, v100
	v_and_b32_e32 v101, 0x7fffffff, v104
	v_and_b32_e32 v100, 0x7fffffff, v105
	v_and_b32_e32 v103, 0x7fffffff, v115
	v_and_b32_e32 v102, 0x7fffffff, v114
	v_and_b32_e32 v105, 0x7fffffff, v113
	v_and_b32_e32 v104, 0x7fffffff, v107
	v_and_b32_e32 v107, 0x7fffffff, v106
	v_and_b32_e32 v106, 0x7fffffff, v109
	v_and_b32_e32 v109, 0x7fffffff, v108
	v_and_b32_e32 v108, 0x7fffffff, v111
	v_and_b32_e32 v111, 0x7fffffff, v110
	v_and_b32_e32 v110, 0x7fffffff, v112
	v_pk_fma_f32 v[78:79], v[160:161], v[110:111], v[78:79] op_sel_hi:[0,1,1] neg_lo:[1,0,0] neg_hi:[1,0,0]
	v_pk_fma_f32 v[76:77], v[160:161], v[108:109], v[76:77] op_sel_hi:[0,1,1] neg_lo:[1,0,0] neg_hi:[1,0,0]
	v_pk_fma_f32 v[74:75], v[160:161], v[106:107], v[74:75] op_sel_hi:[0,1,1] neg_lo:[1,0,0] neg_hi:[1,0,0]
	v_pk_fma_f32 v[72:73], v[160:161], v[104:105], v[72:73] op_sel_hi:[0,1,1] neg_lo:[1,0,0] neg_hi:[1,0,0]
	v_pk_fma_f32 v[70:71], v[160:161], v[102:103], v[70:71] op_sel_hi:[0,1,1] neg_lo:[1,0,0] neg_hi:[1,0,0]
	v_pk_fma_f32 v[68:69], v[160:161], v[100:101], v[68:69] op_sel_hi:[0,1,1] neg_lo:[1,0,0] neg_hi:[1,0,0]
	v_pk_fma_f32 v[66:67], v[160:161], v[98:99], v[66:67] op_sel_hi:[0,1,1] neg_lo:[1,0,0] neg_hi:[1,0,0]
	v_pk_fma_f32 v[64:65], v[160:161], v[96:97], v[64:65] op_sel_hi:[0,1,1] neg_lo:[1,0,0] neg_hi:[1,0,0]
	s_waitcnt vmcnt(0) lgkmcnt(0)
	s_barrier
	v_add_f32_e32 v188, 0, v116
	s_cmp_lt_i32 s70, 4
	s_cbranch_scc1 .LBB0_261
	s_mov_b32 s76, 4
	.p2align	6

.LBB0_272:
	v_add_u32_e32 v140, s83, v229
	v_subrev_u32_e32 v141, 32, v140
	v_min_i32_e32 v112, s79, v141
	v_cmp_lt_i32_e32 vcc, -1, v141
	v_subrev_u32_e32 v120, 24, v140
	v_min_i32_e32 v120, s79, v120
	v_cndmask_b32_e32 v112, 0, v112, vcc
	v_cmp_lt_i32_e32 vcc, -9, v141
	v_add_u32_e32 v132, -16, v140
	v_min_i32_e32 v132, s79, v132
	v_cndmask_b32_e32 v120, 0, v120, vcc
	v_cmp_lt_i32_e32 vcc, s66, v141
	v_add_u32_e32 v140, -8, v140
	v_min_i32_e32 v140, s79, v140
	v_cndmask_b32_e32 v132, 0, v132, vcc
	v_cmp_lt_i32_e32 vcc, s67, v141
	v_lshlrev_b32_e32 v112, s76, v112
	v_lshlrev_b32_e32 v120, s76, v120
	v_cndmask_b32_e32 v140, 0, v140, vcc
	v_lshlrev_b32_e32 v132, s76, v132
	v_lshlrev_b32_e32 v140, s76, v140
	v_add_u32_e32 v112, s77, v112
	v_add_u32_e32 v120, s77, v120
	v_add_u32_e32 v132, s77, v132
	v_add_u32_e32 v140, s77, v140
	v_ashrrev_i32_e32 v113, 31, v112
	v_ashrrev_i32_e32 v121, 31, v120
	v_ashrrev_i32_e32 v133, 31, v132
	v_ashrrev_i32_e32 v141, 31, v140
	v_lshlrev_b64 v[112:113], 7, v[112:113]
	v_lshlrev_b64 v[120:121], 7, v[120:121]
	v_lshlrev_b64 v[132:133], 7, v[132:133]
	v_lshlrev_b64 v[140:141], 7, v[140:141]
	v_lshl_add_u64 v[114:115], v[128:129], 0, v[112:113]
	v_lshl_add_u64 v[112:113], v[184:185], 0, v[112:113]
	v_lshl_add_u64 v[122:123], v[128:129], 0, v[120:121]
	v_lshl_add_u64 v[120:121], v[184:185], 0, v[120:121]
	v_lshl_add_u64 v[134:135], v[128:129], 0, v[132:133]
	v_lshl_add_u64 v[132:133], v[184:185], 0, v[132:133]
	v_lshl_add_u64 v[142:143], v[128:129], 0, v[140:141]
	v_lshl_add_u64 v[140:141], v[184:185], 0, v[140:141]
	global_load_dwordx4 v[116:119], v[114:115], off
	s_nop 0
	global_load_dwordx4 v[112:115], v[112:113], off
	s_nop 0
	global_load_dwordx4 v[124:127], v[122:123], off
	s_nop 0
	global_load_dwordx4 v[120:123], v[120:121], off
	s_nop 0
	global_load_dwordx4 v[136:139], v[134:135], off
	s_nop 0
	global_load_dwordx4 v[132:135], v[132:133], off
	s_nop 0
	global_load_dwordx4 v[144:147], v[142:143], off
	s_nop 0
	global_load_dwordx4 v[140:143], v[140:141], off
	.p2align	6

.LBB0_299:
	s_sub_i32 s8, 4, s74
	v_cvt_f32_u32_e32 v38, s8
	v_lshlrev_b32_e32 v34, 1, v34
	v_lshlrev_b32_e32 v158, 3, v33
	v_and_b32_e32 v34, 2, v34
	v_and_b32_e32 v37, 1, v37
	v_lshlrev_b32_e32 v33, 1, v33
	v_mul_f32_e32 v38, -2.0, v38
	v_bitop3_b32 v40, v34, v33, v37 bitop3:0x36
	v_or_b32_e32 v33, 1, v33
	v_and_b32_e32 v157, 63, v32
	v_exp_f32_e32 v38, v38
	v_bitop3_b32 v33, v34, v33, v37 bitop3:0x36
	v_cvt_f32_ubyte0_e32 v34, v35
	v_cvt_pk_bf16_f32 v34, v34, v34
	v_cmp_gt_u32_e32 vcc, 32, v157
	v_mul_f32_e32 v160, 0x3fb8aa3b, v38
	s_add_i32 s78, s73, 0xc000
	v_cndmask_b32_e32 v152, 0, v34, vcc
	v_or_b32_e32 v34, 32, v35
	v_cvt_f32_ubyte0_e32 v34, v34
	v_cvt_pk_bf16_f32 v34, v34, v34
	v_cndmask_b32_e32 v148, 0, v34, vcc
	v_cvt_pk_bf16_f32 v34, v160, 0
	v_lshlrev_b32_e32 v34, 16, v34
	v_fma_f32 v35, v38, s39, -v34
	v_cvt_pk_bf16_f32 v35, v35, 0
	v_lshlrev_b32_e32 v35, 16, v35
	v_cvt_pk_bf16_f32 v186, v34, v35
	v_xor_b32_e32 v34, 0x80000000, v34
	v_xor_b32_e32 v35, 0x80000000, v35
	v_cvt_pk_bf16_f32 v187, v34, v35
	v_or_b32_e32 v34, s5, v158
	v_sub_u32_e32 v35, v159, v34
	v_xad_u32 v34, v34, -1, v159
	v_cvt_f32_i32_e32 v34, v34
	v_add_u32_e32 v38, -2, v35
	v_add_u32_e32 v44, -3, v35
	v_cvt_f32_i32_e32 v37, v35
	v_cvt_f32_i32_e32 v38, v38
	v_cvt_f32_i32_e32 v44, v44
	v_fma_f32 v17, -v160, |v34|, v17
	v_add_u32_e32 v34, -4, v35
	v_cvt_f32_i32_e32 v34, v34
	v_fma_f32 v16, -v160, |v37|, v16
	v_fma_f32 v18, -v160, |v38|, v18
	v_fma_f32 v19, -v160, |v44|, v19
	v_add_u32_e32 v37, -5, v35
	v_add_u32_e32 v38, -6, v35
	v_add_u32_e32 v44, -7, v35
	v_cvt_f32_i32_e32 v37, v37
	v_cvt_f32_i32_e32 v38, v38
	v_cvt_f32_i32_e32 v44, v44
	v_fma_f32 v34, -v160, |v34|, v20
	v_add_u32_e32 v20, -16, v35
	v_cvt_f32_i32_e32 v20, v20
	v_fma_f32 v37, -v160, |v37|, v21
	v_fma_f32 v38, -v160, |v38|, v22
	v_fma_f32 v44, -v160, |v44|, v23
	v_subrev_u32_e32 v21, 17, v35
	v_subrev_u32_e32 v22, 18, v35
	v_subrev_u32_e32 v23, 19, v35
	v_cvt_f32_i32_e32 v21, v21
	v_cvt_f32_i32_e32 v22, v22
	v_cvt_f32_i32_e32 v23, v23
	v_fma_f32 v45, -v160, |v20|, v24
	v_subrev_u32_e32 v20, 20, v35
	v_cvt_f32_i32_e32 v20, v20
	v_fma_f32 v46, -v160, |v21|, v25
	v_fma_f32 v47, -v160, |v22|, v26
	v_fma_f32 v48, -v160, |v23|, v27
	v_subrev_u32_e32 v21, 21, v35
	v_subrev_u32_e32 v22, 22, v35
	v_subrev_u32_e32 v23, 23, v35
	v_cvt_f32_i32_e32 v21, v21
	v_cvt_f32_i32_e32 v22, v22
	v_cvt_f32_i32_e32 v23, v23
	v_fma_f32 v49, -v160, |v20|, v28
	v_subrev_u32_e32 v20, 32, v35
	v_cvt_f32_i32_e32 v20, v20
	v_fma_f32 v50, -v160, |v21|, v29
	v_fma_f32 v51, -v160, |v22|, v30
	v_fma_f32 v52, -v160, |v23|, v31
	v_subrev_u32_e32 v21, 33, v35
	v_subrev_u32_e32 v22, 34, v35
	v_subrev_u32_e32 v23, 35, v35
	v_cvt_f32_i32_e32 v21, v21
	v_cvt_f32_i32_e32 v22, v22
	v_cvt_f32_i32_e32 v23, v23
	v_fma_f32 v53, -v160, |v20|, v0
	v_subrev_u32_e32 v0, 36, v35
	v_cvt_f32_i32_e32 v0, v0
	v_fma_f32 v54, -v160, |v21|, v1
	v_fma_f32 v120, -v160, |v22|, v2
	v_fma_f32 v121, -v160, |v23|, v3
	v_subrev_u32_e32 v1, 37, v35
	v_subrev_u32_e32 v2, 38, v35
	v_subrev_u32_e32 v3, 39, v35
	v_cvt_f32_i32_e32 v1, v1
	v_cvt_f32_i32_e32 v2, v2
	v_cvt_f32_i32_e32 v3, v3
	v_fma_f32 v122, -v160, |v0|, v4
	v_subrev_u32_e32 v0, 48, v35
	v_cvt_f32_i32_e32 v0, v0
	v_fma_f32 v123, -v160, |v1|, v5
	v_fma_f32 v124, -v160, |v2|, v6
	v_fma_f32 v125, -v160, |v3|, v7
	v_subrev_u32_e32 v1, 49, v35
	v_subrev_u32_e32 v2, 50, v35
	v_subrev_u32_e32 v3, 51, v35
	v_cvt_f32_i32_e32 v1, v1
	v_cvt_f32_i32_e32 v2, v2
	v_cvt_f32_i32_e32 v3, v3
	v_fma_f32 v128, -v160, |v0|, v8
	v_subrev_u32_e32 v0, 52, v35
	v_cvt_f32_i32_e32 v0, v0
	v_fma_f32 v129, -v160, |v1|, v9
	v_fma_f32 v130, -v160, |v2|, v10
	v_fma_f32 v192, -v160, |v3|, v11
	v_subrev_u32_e32 v1, 53, v35
	v_subrev_u32_e32 v2, 54, v35
	v_subrev_u32_e32 v3, 55, v35
	v_cvt_f32_i32_e32 v1, v1
	v_cvt_f32_i32_e32 v2, v2
	v_cvt_f32_i32_e32 v3, v3
	s_lshl_b32 s5, s4, 14
	v_fma_f32 v204, -v160, |v0|, v12
	v_add_u32_e32 v0, s5, v170
	s_mov_b32 s8, m0
	s_mov_b32 m0, s78
	s_nop 0
	global_load_lds_dwordx4 v0, s[6:7]
	s_mov_b32 m0, s8
	v_add_u32_e32 v0, s5, v169
	s_add_i32 s79, s73, 0xe000
	s_mov_b32 s5, m0
	s_mov_b32 m0, s79
	s_nop 0
	global_load_lds_dwordx4 v0, s[6:7]
	s_mov_b32 m0, s5
	v_exp_f32_e32 v35, v16
	v_fma_f32 v205, -v160, |v1|, v13
	v_fma_f32 v206, -v160, |v2|, v14
	v_fma_f32 v207, -v160, |v3|, v15
	ds_read_b128 v[0:3], v171 offset:32768
	ds_read_b128 v[4:7], v171 offset:36864
	ds_read_b128 v[8:11], v174 offset:32768
	ds_read_b128 v[12:15], v174 offset:36864
	v_exp_f32_e32 v55, v17
	v_exp_f32_e32 v56, v18
	v_exp_f32_e32 v57, v19
	v_add_f32_e32 v16, 0, v35
	v_lshrrev_b32_e32 v36, 2, v36
	v_add_f32_e32 v16, v55, v16
	v_or_b32_e32 v39, v158, v36
	v_lshlrev_b32_e32 v32, 3, v32
	v_lshlrev_b32_e32 v36, 6, v36
	v_cndmask_b32_e32 v154, 0, v196, vcc
	v_cndmask_b32_e32 v153, 0, v197, vcc
	v_add_f32_e32 v16, v56, v16
	s_mov_b32 s74, 2
	v_and_b32_e32 v32, 8, v32
	v_xor_b32_e32 v41, 64, v36
	v_xor_b32_e32 v42, 0x80, v36
	v_xor_b32_e32 v43, 0xc0, v36
	v_lshlrev_b32_e32 v33, 4, v33
	v_mov_b32_e32 v155, v131
	v_mov_b32_e32 v149, v153
	v_mov_b32_e32 v150, v154
	v_mov_b32_e32 v151, v131
	v_add_f32_e32 v58, v57, v16
	s_waitcnt lgkmcnt(3)
	v_mfma_f32_32x32x16_bf16 v[80:95], v[0:3], v[144:147], 0
	ds_read_b128 v[16:19], v172 offset:32768
	ds_read_b128 v[20:23], v172 offset:36864
	ds_read_b128 v[24:27], v173 offset:32768
	ds_read_b128 v[28:31], v173 offset:36864
	v_exp_f32_e32 v34, v34
	v_exp_f32_e32 v37, v37
	v_add_f32_e32 v0, v34, v58
	v_add_f32_e32 v2, v37, v0
	s_waitcnt lgkmcnt(6)
	v_mfma_f32_32x32x16_bf16 v[64:79], v[4:7], v[144:147], 0
	v_exp_f32_e32 v3, v38
	v_exp_f32_e32 v38, v44
	v_cvt_pk_bf16_f32 v0, v35, v55
	v_cvt_pk_bf16_f32 v1, v56, v57
	v_add_f32_e32 v2, v3, v2
	v_add_f32_e32 v35, v38, v2
	v_cvt_pk_bf16_f32 v2, v34, v37
	v_cvt_pk_bf16_f32 v3, v3, v38
	s_waitcnt lgkmcnt(5)
	v_mfma_f32_32x32x16_bf16 v[80:95], v[8:11], v[140:143], v[80:95]
	v_exp_f32_e32 v34, v45
	v_exp_f32_e32 v37, v46
	v_add_f32_e32 v4, v34, v35
	v_add_f32_e32 v4, v37, v4
	s_waitcnt lgkmcnt(4)
	v_mfma_f32_32x32x16_bf16 v[64:79], v[12:15], v[140:143], v[64:79]
	v_exp_f32_e32 v35, v47
	v_exp_f32_e32 v38, v48
	v_add_f32_e32 v4, v35, v4
	v_add_f32_e32 v44, v38, v4
	v_lshl_or_b32 v4, v39, 8, v32
	v_lshl_or_b32 v12, v40, 4, v4
	v_or_b32_e32 v165, v12, v36
	v_add_u32_e32 v13, 0x400, v4
	v_or_b32_e32 v161, v12, v42
	v_add_u32_e32 v175, 0, v165
	v_or3_b32 v166, v33, v36, v13
	v_or_b32_e32 v167, v12, v41
	v_or3_b32 v168, v33, v41, v13
	v_add_u32_e32 v179, 0, v161
	v_or3_b32 v162, v33, v42, v13
	v_or_b32_e32 v163, v12, v43
	v_or3_b32 v164, v33, v43, v13
	s_waitcnt lgkmcnt(3)
	v_mfma_f32_32x32x16_bf16 v[80:95], v[16:19], v[136:139], v[80:95]
	v_add_u32_e32 v176, 0, v166
	v_add_u32_e32 v177, 0, v167
	v_add_u32_e32 v178, 0, v168
	ds_read_b64_tr_b16 v[4:5], v175 offset:16384
	ds_read_b64_tr_b16 v[6:7], v176 offset:16384
	ds_read_b64_tr_b16 v[8:9], v177 offset:16384
	ds_read_b64_tr_b16 v[10:11], v178 offset:16384
	v_add_u32_e32 v182, 0, v162
	v_add_u32_e32 v183, 0, v163
	v_add_u32_e32 v184, 0, v164
	ds_read_b64_tr_b16 v[12:13], v179 offset:16384
	ds_read_b64_tr_b16 v[14:15], v182 offset:16384
	ds_read_b64_tr_b16 v[96:97], v183 offset:16384
	ds_read_b64_tr_b16 v[98:99], v184 offset:16384
	v_exp_f32_e32 v32, v49
	v_exp_f32_e32 v33, v50
	v_add_f32_e32 v16, v32, v44
	v_add_f32_e32 v16, v33, v16
	s_waitcnt lgkmcnt(10)
	v_mfma_f32_32x32x16_bf16 v[64:79], v[20:23], v[136:139], v[64:79]
	v_exp_f32_e32 v17, v51
	v_exp_f32_e32 v18, v52
	v_cvt_pk_bf16_f32 v100, v34, v37
	v_cvt_pk_bf16_f32 v101, v35, v38
	v_add_f32_e32 v16, v17, v16
	v_add_f32_e32 v16, v18, v16
	v_cvt_pk_bf16_f32 v102, v32, v33
	v_cvt_pk_bf16_f32 v103, v17, v18
	s_waitcnt lgkmcnt(9)
	v_mfma_f32_32x32x16_bf16 v[80:95], v[24:27], v[132:135], v[80:95]
	s_waitcnt lgkmcnt(8)
	v_mfma_f32_32x32x16_bf16 v[64:79], v[28:31], v[132:135], v[64:79]
	ds_read_b64_tr_b16 v[104:105], v175 offset:20480
	ds_read_b64_tr_b16 v[106:107], v176 offset:20480
	ds_read_b64_tr_b16 v[108:109], v177 offset:20480
	ds_read_b64_tr_b16 v[110:111], v178 offset:20480
	ds_read_b64_tr_b16 v[112:113], v179 offset:20480
	ds_read_b64_tr_b16 v[114:115], v182 offset:20480
	ds_read_b64_tr_b16 v[116:117], v183 offset:20480
	ds_read_b64_tr_b16 v[118:119], v184 offset:20480
	v_exp_f32_e32 v126, v53
	v_exp_f32_e32 v127, v54
	s_waitcnt lgkmcnt(14)
	v_mfma_f32_32x32x16_bf16 v[48:63], v[4:7], v[0:3], 0
	v_lshl_or_b32 v17, s4, 6, v158
	v_add_f32_e32 v4, v126, v16
	v_add_f32_e32 v4, v127, v4
	v_sub_u32_e32 v208, v159, v17
	v_add_u32_e32 v209, -1, v208
	s_waitcnt lgkmcnt(12)
	v_mfma_f32_32x32x16_bf16 v[32:47], v[8:11], v[0:3], 0
	v_exp_f32_e32 v5, v120
	v_exp_f32_e32 v6, v121
	v_add_u32_e32 v210, -3, v208
	v_add_u32_e32 v211, -2, v208
	v_add_f32_e32 v4, v5, v4
	v_add_f32_e32 v4, v6, v4
	s_waitcnt lgkmcnt(10)
	v_mfma_f32_32x32x16_bf16 v[16:31], v[12:15], v[0:3], 0
	v_exp_f32_e32 v122, v122
	v_exp_f32_e32 v123, v123
	v_add_u32_e32 v212, -5, v208
	v_add_u32_e32 v213, -4, v208
	v_add_f32_e32 v4, v122, v4
	v_add_f32_e32 v4, v123, v4
	v_exp_f32_e32 v124, v124
	v_exp_f32_e32 v125, v125
	v_cvt_pk_bf16_f32 v121, v5, v6
	v_cvt_pk_bf16_f32 v120, v126, v127
	v_add_f32_e32 v4, v124, v4
	v_add_f32_e32 v214, v125, v4
	s_waitcnt lgkmcnt(8)
	v_mfma_f32_32x32x16_bf16 v[0:15], v[96:99], v[0:3], 0
	v_cvt_pk_bf16_f32 v122, v122, v123
	v_cvt_pk_bf16_f32 v123, v124, v125
	v_add_u32_e32 v215, -7, v208
	v_add_u32_e32 v216, -6, v208
	ds_read_b64_tr_b16 v[96:97], v175 offset:24576
	ds_read_b64_tr_b16 v[98:99], v176 offset:24576
	ds_read_b64_tr_b16 v[124:125], v177 offset:24576
	ds_read_b64_tr_b16 v[126:127], v178 offset:24576
	ds_read_b64_tr_b16 v[188:189], v179 offset:24576
	ds_read_b64_tr_b16 v[190:191], v182 offset:24576
	ds_read_b64_tr_b16 v[200:201], v183 offset:24576
	ds_read_b64_tr_b16 v[202:203], v184 offset:24576
	s_waitcnt lgkmcnt(14)
	v_mfma_f32_32x32x16_bf16 v[48:63], v[104:107], v[100:103], v[48:63]
	v_exp_f32_e32 v128, v128
	v_subrev_u32_e32 v105, 17, v208
	v_add_u32_e32 v106, -16, v208
	v_add_f32_e32 v104, v128, v214
	s_waitcnt lgkmcnt(12)
	v_mfma_f32_32x32x16_bf16 v[32:47], v[108:111], v[100:103], v[32:47]
	v_exp_f32_e32 v129, v129
	v_subrev_u32_e32 v107, 19, v208
	v_subrev_u32_e32 v214, 18, v208
	v_add_f32_e32 v104, v129, v104
	s_waitcnt lgkmcnt(10)
	v_mfma_f32_32x32x16_bf16 v[16:31], v[112:115], v[100:103], v[16:31]
	v_exp_f32_e32 v130, v130
	v_subrev_u32_e32 v108, 21, v208
	v_subrev_u32_e32 v109, 20, v208
	v_add_f32_e32 v104, v130, v104
	v_exp_f32_e32 v192, v192
	s_waitcnt lgkmcnt(8)
	v_mfma_f32_32x32x16_bf16 v[0:15], v[116:119], v[100:103], v[0:15]
	v_subrev_u32_e32 v110, 23, v208
	v_subrev_u32_e32 v111, 22, v208
	v_cvt_f32_i32_e32 v114, v111
	v_add_f32_e32 v217, v192, v104
	v_cvt_f32_i32_e32 v115, v110
	v_cvt_f32_i32_e32 v112, v109
	v_cvt_f32_i32_e32 v113, v108
	v_cvt_f32_i32_e32 v110, v214
	v_cvt_f32_i32_e32 v111, v107
	v_cvt_f32_i32_e32 v108, v106
	v_cvt_f32_i32_e32 v109, v105
	v_cvt_f32_i32_e32 v106, v216
	v_cvt_f32_i32_e32 v107, v215
	v_cvt_f32_i32_e32 v104, v213
	v_cvt_f32_i32_e32 v105, v212
	v_cvt_f32_i32_e32 v100, v208
	v_cvt_f32_i32_e32 v101, v209
	v_cvt_f32_i32_e32 v102, v210
	v_cvt_f32_i32_e32 v116, v211
	v_and_b32_e32 v100, 0x7fffffff, v100
	v_and_b32_e32 v101, 0x7fffffff, v101
	v_and_b32_e32 v103, 0x7fffffff, v102
	v_and_b32_e32 v102, 0x7fffffff, v116
	v_and_b32_e32 v105, 0x7fffffff, v105
	v_and_b32_e32 v104, 0x7fffffff, v104
	v_and_b32_e32 v107, 0x7fffffff, v107
	v_and_b32_e32 v106, 0x7fffffff, v106
	v_and_b32_e32 v109, 0x7fffffff, v109
	v_and_b32_e32 v108, 0x7fffffff, v108
	v_and_b32_e32 v111, 0x7fffffff, v111
	v_and_b32_e32 v110, 0x7fffffff, v110
	v_and_b32_e32 v113, 0x7fffffff, v113
	v_and_b32_e32 v112, 0x7fffffff, v112
	v_and_b32_e32 v115, 0x7fffffff, v115
	v_and_b32_e32 v114, 0x7fffffff, v114
	v_pk_fma_f32 v[94:95], v[160:161], v[114:115], v[94:95] op_sel_hi:[0,1,1] neg_lo:[1,0,0] neg_hi:[1,0,0]
	v_pk_fma_f32 v[92:93], v[160:161], v[112:113], v[92:93] op_sel_hi:[0,1,1] neg_lo:[1,0,0] neg_hi:[1,0,0]
	v_pk_fma_f32 v[90:91], v[160:161], v[110:111], v[90:91] op_sel_hi:[0,1,1] neg_lo:[1,0,0] neg_hi:[1,0,0]
	v_pk_fma_f32 v[88:89], v[160:161], v[108:109], v[88:89] op_sel_hi:[0,1,1] neg_lo:[1,0,0] neg_hi:[1,0,0]
	v_pk_fma_f32 v[86:87], v[160:161], v[106:107], v[86:87] op_sel_hi:[0,1,1] neg_lo:[1,0,0] neg_hi:[1,0,0]
	v_pk_fma_f32 v[84:85], v[160:161], v[104:105], v[84:85] op_sel_hi:[0,1,1] neg_lo:[1,0,0] neg_hi:[1,0,0]
	v_pk_fma_f32 v[82:83], v[160:161], v[102:103], v[82:83] op_sel_hi:[0,1,1] neg_lo:[1,0,0] neg_hi:[1,0,0]
	v_pk_fma_f32 v[80:81], v[160:161], v[100:101], v[80:81] op_sel_hi:[0,1,1] neg_lo:[1,0,0] neg_hi:[1,0,0]
	ds_read_b64_tr_b16 v[100:101], v175 offset:28672
	ds_read_b64_tr_b16 v[102:103], v176 offset:28672
	ds_read_b64_tr_b16 v[104:105], v177 offset:28672
	ds_read_b64_tr_b16 v[106:107], v178 offset:28672
	ds_read_b64_tr_b16 v[108:109], v179 offset:28672
	ds_read_b64_tr_b16 v[110:111], v182 offset:28672
	ds_read_b64_tr_b16 v[112:113], v183 offset:28672
	ds_read_b64_tr_b16 v[114:115], v184 offset:28672
	s_waitcnt lgkmcnt(14)
	v_mfma_f32_32x32x16_bf16 v[48:63], v[96:99], v[120:123], v[48:63]
	v_exp_f32_e32 v116, v204
	s_nop 0
	v_add_f32_e32 v96, v116, v217
	s_waitcnt lgkmcnt(12)
	v_mfma_f32_32x32x16_bf16 v[32:47], v[124:127], v[120:123], v[32:47]
	v_exp_f32_e32 v98, v205
	s_nop 0
	v_add_f32_e32 v96, v98, v96
	s_waitcnt lgkmcnt(10)
	v_mfma_f32_32x32x16_bf16 v[16:31], v[188:191], v[120:123], v[16:31]
	v_exp_f32_e32 v99, v206
	s_nop 0
	v_add_f32_e32 v117, v99, v96
	s_waitcnt lgkmcnt(8)
	v_mfma_f32_32x32x16_bf16 v[0:15], v[200:203], v[120:123], v[0:15]
	v_exp_f32_e32 v118, v207
	v_cvt_pk_bf16_f32 v96, v128, v129
	v_cvt_pk_bf16_f32 v97, v130, v192
	v_cvt_pk_bf16_f32 v98, v116, v98
	v_add_f32_e32 v116, v118, v117
	v_cvt_pk_bf16_f32 v99, v99, v118
	s_waitcnt lgkmcnt(6)
	s_nop 0
	v_mfma_f32_32x32x16_bf16 v[48:63], v[100:103], v[96:99], v[48:63]
	s_waitcnt lgkmcnt(4)
	v_mfma_f32_32x32x16_bf16 v[32:47], v[104:107], v[96:99], v[32:47]
	s_waitcnt lgkmcnt(2)
	v_mfma_f32_32x32x16_bf16 v[16:31], v[108:111], v[96:99], v[16:31]
	s_waitcnt lgkmcnt(0)
	v_mfma_f32_32x32x16_bf16 v[0:15], v[112:115], v[96:99], v[0:15]
	v_subrev_u32_e32 v100, 33, v208
	v_subrev_u32_e32 v101, 32, v208
	v_subrev_u32_e32 v102, 35, v208
	v_subrev_u32_e32 v103, 34, v208
	v_subrev_u32_e32 v104, 37, v208
	v_subrev_u32_e32 v105, 36, v208
	v_subrev_u32_e32 v96, 39, v208
	v_subrev_u32_e32 v97, 38, v208
	v_subrev_u32_e32 v98, 49, v208
	v_subrev_u32_e32 v99, 48, v208
	v_subrev_u32_e32 v106, 51, v208
	v_subrev_u32_e32 v107, 50, v208
	v_subrev_u32_e32 v108, 53, v208
	v_subrev_u32_e32 v109, 52, v208
	v_subrev_u32_e32 v110, 55, v208
	v_subrev_u32_e32 v111, 54, v208
	v_cvt_f32_i32_e32 v112, v111
	v_cvt_f32_i32_e32 v110, v110
	v_cvt_f32_i32_e32 v111, v109
	v_cvt_f32_i32_e32 v108, v108
	v_cvt_f32_i32_e32 v109, v107
	v_cvt_f32_i32_e32 v106, v106
	v_cvt_f32_i32_e32 v107, v99
	v_cvt_f32_i32_e32 v113, v98
	v_cvt_f32_i32_e32 v114, v97
	v_cvt_f32_i32_e32 v115, v96
	v_cvt_f32_i32_e32 v105, v105
	v_cvt_f32_i32_e32 v104, v104
	v_cvt_f32_i32_e32 v96, v100
	v_cvt_f32_i32_e32 v98, v101
	v_cvt_f32_i32_e32 v99, v102
	v_cvt_f32_i32_e32 v100, v103
	v_and_b32_e32 v97, 0x7fffffff, v96
	v_and_b32_e32 v96, 0x7fffffff, v98
	v_and_b32_e32 v99, 0x7fffffff, v99
	v_and_b32_e32 v98, 0x7fffffff, v100
	v_and_b32_e32 v101, 0x7fffffff, v104
	v_and_b32_e32 v100, 0x7fffffff, v105
	v_and_b32_e32 v103, 0x7fffffff, v115
	v_and_b32_e32 v102, 0x7fffffff, v114
	v_and_b32_e32 v105, 0x7fffffff, v113
	v_and_b32_e32 v104, 0x7fffffff, v107
	v_and_b32_e32 v107, 0x7fffffff, v106
	v_and_b32_e32 v106, 0x7fffffff, v109
	v_and_b32_e32 v109, 0x7fffffff, v108
	v_and_b32_e32 v108, 0x7fffffff, v111
	v_and_b32_e32 v111, 0x7fffffff, v110
	v_and_b32_e32 v110, 0x7fffffff, v112
	v_pk_fma_f32 v[78:79], v[160:161], v[110:111], v[78:79] op_sel_hi:[0,1,1] neg_lo:[1,0,0] neg_hi:[1,0,0]
	v_pk_fma_f32 v[76:77], v[160:161], v[108:109], v[76:77] op_sel_hi:[0,1,1] neg_lo:[1,0,0] neg_hi:[1,0,0]
	v_pk_fma_f32 v[74:75], v[160:161], v[106:107], v[74:75] op_sel_hi:[0,1,1] neg_lo:[1,0,0] neg_hi:[1,0,0]
	v_pk_fma_f32 v[72:73], v[160:161], v[104:105], v[72:73] op_sel_hi:[0,1,1] neg_lo:[1,0,0] neg_hi:[1,0,0]
	v_pk_fma_f32 v[70:71], v[160:161], v[102:103], v[70:71] op_sel_hi:[0,1,1] neg_lo:[1,0,0] neg_hi:[1,0,0]
	v_pk_fma_f32 v[68:69], v[160:161], v[100:101], v[68:69] op_sel_hi:[0,1,1] neg_lo:[1,0,0] neg_hi:[1,0,0]
	v_pk_fma_f32 v[66:67], v[160:161], v[98:99], v[66:67] op_sel_hi:[0,1,1] neg_lo:[1,0,0] neg_hi:[1,0,0]
	v_pk_fma_f32 v[64:65], v[160:161], v[96:97], v[64:65] op_sel_hi:[0,1,1] neg_lo:[1,0,0] neg_hi:[1,0,0]
	s_waitcnt vmcnt(0) lgkmcnt(0)
	s_barrier
	v_add_f32_e32 v188, 0, v116
	s_cmp_lt_i32 s20, 4
	s_cbranch_scc1 .LBB0_305
	s_mov_b32 s74, 4
	.p2align	6

.LBB0_381:
	s_ashr_i32 s37, s36, 31
	s_lshl_b64 s[38:39], s[36:37], 19
	s_add_u32 s38, s18, s38
	s_addc_u32 s39, s19, s39
	s_and_b64 s[40:41], s[4:5], exec
	s_cselect_b32 s37, s39, s47
	s_cselect_b32 s45, s38, s46
	s_ashr_i32 s29, s28, 31
	s_lshl_b64 s[40:41], s[28:29], 19
	s_add_u32 s40, s42, s40
	s_addc_u32 s41, s43, s41
	s_and_b64 s[50:51], s[4:5], exec
	s_cselect_b32 s29, s41, s49
	s_cselect_b32 s69, s40, s48
	s_add_u32 s46, s46, 0x40080
	s_addc_u32 s47, s47, 0
	s_add_u32 s70, s48, 0x100
	v_mov_b32_e32 v0, 0
	s_addc_u32 s71, s49, 0
	s_mov_b32 s72, -2
	s_waitcnt lgkmcnt(0)
	v_mov_b32_e32 v1, v0
	v_mov_b32_e32 v2, v0
	v_mov_b32_e32 v3, v0
	v_mov_b32_e32 v4, v0
	v_mov_b32_e32 v5, v0
	v_mov_b32_e32 v6, v0
	v_mov_b32_e32 v7, v0
	v_mov_b32_e32 v16, v0
	v_mov_b32_e32 v17, v0
	v_mov_b32_e32 v18, v0
	v_mov_b32_e32 v19, v0
	v_mov_b32_e32 v20, v0
	v_mov_b32_e32 v21, v0
	v_mov_b32_e32 v22, v0
	v_mov_b32_e32 v23, v0
	v_mov_b32_e32 v32, v0
	v_mov_b32_e32 v33, v0
	v_mov_b32_e32 v34, v0
	v_mov_b32_e32 v35, v0
	v_mov_b32_e32 v36, v0
	v_mov_b32_e32 v37, v0
	v_mov_b32_e32 v38, v0
	v_mov_b32_e32 v39, v0
	v_mov_b32_e32 v48, v0
	v_mov_b32_e32 v49, v0
	v_mov_b32_e32 v50, v0
	v_mov_b32_e32 v51, v0
	v_mov_b32_e32 v52, v0
	v_mov_b32_e32 v53, v0
	v_mov_b32_e32 v54, v0
	v_mov_b32_e32 v55, v0
	v_mov_b32_e32 v8, v0
	v_mov_b32_e32 v9, v0
	v_mov_b32_e32 v10, v0
	v_mov_b32_e32 v11, v0
	v_mov_b32_e32 v12, v0
	v_mov_b32_e32 v13, v0
	v_mov_b32_e32 v14, v0
	v_mov_b32_e32 v15, v0
	v_mov_b32_e32 v24, v0
	v_mov_b32_e32 v25, v0
	v_mov_b32_e32 v26, v0
	v_mov_b32_e32 v27, v0
	v_mov_b32_e32 v28, v0
	v_mov_b32_e32 v29, v0
	v_mov_b32_e32 v30, v0
	v_mov_b32_e32 v31, v0
	v_mov_b32_e32 v40, v0
	v_mov_b32_e32 v41, v0
	v_mov_b32_e32 v42, v0
	v_mov_b32_e32 v43, v0
	v_mov_b32_e32 v44, v0
	v_mov_b32_e32 v45, v0
	v_mov_b32_e32 v46, v0
	v_mov_b32_e32 v47, v0
	v_mov_b32_e32 v56, v0
	v_mov_b32_e32 v57, v0
	v_mov_b32_e32 v58, v0
	v_mov_b32_e32 v59, v0
	v_mov_b32_e32 v60, v0
	v_mov_b32_e32 v61, v0
	v_mov_b32_e32 v62, v0
	v_mov_b32_e32 v63, v0
	v_mov_b32_e32 v64, v0
	v_mov_b32_e32 v65, v0
	v_mov_b32_e32 v66, v0
	v_mov_b32_e32 v67, v0
	v_mov_b32_e32 v68, v0
	v_mov_b32_e32 v69, v0
	v_mov_b32_e32 v70, v0
	v_mov_b32_e32 v71, v0
	v_mov_b32_e32 v80, v0
	v_mov_b32_e32 v81, v0
	v_mov_b32_e32 v82, v0
	v_mov_b32_e32 v83, v0
	v_mov_b32_e32 v84, v0
	v_mov_b32_e32 v85, v0
	v_mov_b32_e32 v86, v0
	v_mov_b32_e32 v87, v0
	v_mov_b32_e32 v96, v0
	v_mov_b32_e32 v97, v0
	v_mov_b32_e32 v98, v0
	v_mov_b32_e32 v99, v0
	v_mov_b32_e32 v100, v0
	v_mov_b32_e32 v101, v0
	v_mov_b32_e32 v102, v0
	v_mov_b32_e32 v103, v0
	v_mov_b32_e32 v112, v0
	v_mov_b32_e32 v113, v0
	v_mov_b32_e32 v114, v0
	v_mov_b32_e32 v115, v0
	v_mov_b32_e32 v116, v0
	v_mov_b32_e32 v117, v0
	v_mov_b32_e32 v118, v0
	v_mov_b32_e32 v119, v0
	v_mov_b32_e32 v72, v0
	v_mov_b32_e32 v73, v0
	v_mov_b32_e32 v74, v0
	v_mov_b32_e32 v75, v0
	v_mov_b32_e32 v76, v0
	v_mov_b32_e32 v77, v0
	v_mov_b32_e32 v78, v0
	v_mov_b32_e32 v79, v0
	v_mov_b32_e32 v88, v0
	v_mov_b32_e32 v89, v0
	v_mov_b32_e32 v90, v0
	v_mov_b32_e32 v91, v0
	v_mov_b32_e32 v92, v0
	v_mov_b32_e32 v93, v0
	v_mov_b32_e32 v94, v0
	v_mov_b32_e32 v95, v0
	v_mov_b32_e32 v104, v0
	v_mov_b32_e32 v105, v0
	v_mov_b32_e32 v106, v0
	v_mov_b32_e32 v107, v0
	s_waitcnt vmcnt(0)
	v_mov_b32_e32 v108, v0
	v_mov_b32_e32 v109, v0
	v_mov_b32_e32 v110, v0
	v_mov_b32_e32 v111, v0
	v_mov_b32_e32 v120, v0
	v_mov_b32_e32 v121, v0
	v_mov_b32_e32 v122, v0
	v_mov_b32_e32 v123, v0
	v_mov_b32_e32 v124, v0
	v_mov_b32_e32 v125, v0
	v_mov_b32_e32 v126, v0
	v_mov_b32_e32 v127, v0
	.p2align	6

.LBB0_473:
	s_ashr_i32 s21, s20, 31
	s_lshl_b64 s[22:23], s[20:21], 19
	s_add_u32 s22, s16, s22
	s_addc_u32 s23, s17, s23
	s_and_b64 s[24:25], s[0:1], exec
	s_cselect_b32 s21, s23, s29
	s_cselect_b32 s50, s22, s28
	s_ashr_i32 s19, s18, 31
	s_lshl_b64 s[24:25], s[18:19], 19
	s_add_u32 s24, s34, s24
	s_addc_u32 s25, s35, s25
	s_and_b64 s[38:39], s[0:1], exec
	s_cselect_b32 s19, s25, s37
	s_cselect_b32 s51, s24, s36
	s_add_u32 s28, s28, 0x40080
	s_addc_u32 s29, s29, 0
	s_add_u32 s52, s36, 0x100
	v_mov_b32_e32 v0, 0
	s_addc_u32 s53, s37, 0
	s_mov_b32 s54, -2
	v_mov_b32_e32 v1, v0
	v_mov_b32_e32 v2, v0
	v_mov_b32_e32 v3, v0
	v_mov_b32_e32 v4, v0
	v_mov_b32_e32 v5, v0
	v_mov_b32_e32 v6, v0
	v_mov_b32_e32 v7, v0
	v_mov_b32_e32 v16, v0
	v_mov_b32_e32 v17, v0
	v_mov_b32_e32 v18, v0
	v_mov_b32_e32 v19, v0
	v_mov_b32_e32 v20, v0
	v_mov_b32_e32 v21, v0
	v_mov_b32_e32 v22, v0
	v_mov_b32_e32 v23, v0
	v_mov_b32_e32 v32, v0
	v_mov_b32_e32 v33, v0
	v_mov_b32_e32 v34, v0
	v_mov_b32_e32 v35, v0
	v_mov_b32_e32 v36, v0
	v_mov_b32_e32 v37, v0
	v_mov_b32_e32 v38, v0
	v_mov_b32_e32 v39, v0
	v_mov_b32_e32 v48, v0
	v_mov_b32_e32 v49, v0
	v_mov_b32_e32 v50, v0
	v_mov_b32_e32 v51, v0
	v_mov_b32_e32 v52, v0
	v_mov_b32_e32 v53, v0
	v_mov_b32_e32 v54, v0
	v_mov_b32_e32 v55, v0
	v_mov_b32_e32 v8, v0
	v_mov_b32_e32 v9, v0
	v_mov_b32_e32 v10, v0
	v_mov_b32_e32 v11, v0
	v_mov_b32_e32 v12, v0
	v_mov_b32_e32 v13, v0
	v_mov_b32_e32 v14, v0
	v_mov_b32_e32 v15, v0
	v_mov_b32_e32 v24, v0
	v_mov_b32_e32 v25, v0
	v_mov_b32_e32 v26, v0
	v_mov_b32_e32 v27, v0
	v_mov_b32_e32 v28, v0
	v_mov_b32_e32 v29, v0
	v_mov_b32_e32 v30, v0
	v_mov_b32_e32 v31, v0
	v_mov_b32_e32 v40, v0
	v_mov_b32_e32 v41, v0
	v_mov_b32_e32 v42, v0
	v_mov_b32_e32 v43, v0
	v_mov_b32_e32 v44, v0
	v_mov_b32_e32 v45, v0
	v_mov_b32_e32 v46, v0
	v_mov_b32_e32 v47, v0
	v_mov_b32_e32 v56, v0
	v_mov_b32_e32 v57, v0
	v_mov_b32_e32 v58, v0
	v_mov_b32_e32 v59, v0
	v_mov_b32_e32 v60, v0
	v_mov_b32_e32 v61, v0
	v_mov_b32_e32 v62, v0
	v_mov_b32_e32 v63, v0
	v_mov_b32_e32 v64, v0
	v_mov_b32_e32 v65, v0
	v_mov_b32_e32 v66, v0
	v_mov_b32_e32 v67, v0
	v_mov_b32_e32 v68, v0
	v_mov_b32_e32 v69, v0
	v_mov_b32_e32 v70, v0
	v_mov_b32_e32 v71, v0
	v_mov_b32_e32 v80, v0
	v_mov_b32_e32 v81, v0
	v_mov_b32_e32 v82, v0
	v_mov_b32_e32 v83, v0
	v_mov_b32_e32 v84, v0
	v_mov_b32_e32 v85, v0
	v_mov_b32_e32 v86, v0
	v_mov_b32_e32 v87, v0
	v_mov_b32_e32 v96, v0
	v_mov_b32_e32 v97, v0
	v_mov_b32_e32 v98, v0
	v_mov_b32_e32 v99, v0
	v_mov_b32_e32 v100, v0
	v_mov_b32_e32 v101, v0
	v_mov_b32_e32 v102, v0
	v_mov_b32_e32 v103, v0
	v_mov_b32_e32 v112, v0
	v_mov_b32_e32 v113, v0
	v_mov_b32_e32 v114, v0
	v_mov_b32_e32 v115, v0
	v_mov_b32_e32 v116, v0
	v_mov_b32_e32 v117, v0
	v_mov_b32_e32 v118, v0
	v_mov_b32_e32 v119, v0
	v_mov_b32_e32 v72, v0
	v_mov_b32_e32 v73, v0
	v_mov_b32_e32 v74, v0
	v_mov_b32_e32 v75, v0
	v_mov_b32_e32 v76, v0
	v_mov_b32_e32 v77, v0
	v_mov_b32_e32 v78, v0
	v_mov_b32_e32 v79, v0
	v_mov_b32_e32 v88, v0
	v_mov_b32_e32 v89, v0
	v_mov_b32_e32 v90, v0
	v_mov_b32_e32 v91, v0
	v_mov_b32_e32 v92, v0
	v_mov_b32_e32 v93, v0
	v_mov_b32_e32 v94, v0
	v_mov_b32_e32 v95, v0
	v_mov_b32_e32 v104, v0
	v_mov_b32_e32 v105, v0
	v_mov_b32_e32 v106, v0
	v_mov_b32_e32 v107, v0
	s_waitcnt vmcnt(0)
	v_mov_b32_e32 v108, v0
	v_mov_b32_e32 v109, v0
	v_mov_b32_e32 v110, v0
	v_mov_b32_e32 v111, v0
	v_mov_b32_e32 v120, v0
	v_mov_b32_e32 v121, v0
	v_mov_b32_e32 v122, v0
	v_mov_b32_e32 v123, v0
	v_mov_b32_e32 v124, v0
	v_mov_b32_e32 v125, v0
	v_mov_b32_e32 v126, v0
	v_mov_b32_e32 v127, v0
	.p2align	6
